# hyena latent: also warms the channel's 4 filter rows (64 KB) with one dummy load per thread at the top of each iteration
# speedup vs baseline: 1.0011x; 1.0011x over previous
.LBB0_1341:
	s_or_b64 exec, exec, s[12:13]
	v_readlane_b32 s0, v253, 23
	v_readlane_b32 s1, v253, 24
	s_load_dwordx2 s[38:39], s[0:1], 0x78
	s_waitcnt lgkmcnt(0)
	s_load_dwordx2 s[40:41], s[0:1], 0x80
	s_waitcnt lgkmcnt(0)
	s_load_dwordx2 s[4:5], s[0:1], 0xa8
	s_waitcnt lgkmcnt(0)
	s_load_dwordx2 s[44:45], s[0:1], 0xb0
	s_waitcnt lgkmcnt(0)
	s_cmpk_lt_i32 s76, 0x200
	s_load_dwordx2 s[46:47], s[0:1], 0xb8
	s_waitcnt lgkmcnt(0)
	s_cselect_b64 s[0:1], -1, 0
	v_writelane_b32 v253, s0, 52
	s_cmpk_gt_i32 s76, 0x1ff
	s_cselect_b64 s[2:3], -1, 0
	v_writelane_b32 v253, s1, 53
	s_add_u32 s0, s84, 0x2da00000
	s_addc_u32 s1, s85, 0
	v_writelane_b32 v253, s0, 54
	s_movk_i32 s33, 0x200
	s_nop 0
	v_writelane_b32 v253, s1, 55
	v_writelane_b32 v253, s2, 56
	s_and_b64 vcc, exec, s[2:3]
	s_nop 0
	v_writelane_b32 v253, s3, 57
	v_writelane_b32 v253, s76, 58
	s_nop 1
	v_writelane_b32 v253, s77, 59
	s_cbranch_vccnz .LBB0_1817
	v_writelane_b32 v253, s4, 60
	v_and_b32_e32 v8, 31, v150
	v_lshlrev_b32_e32 v8, 3, v8
	v_writelane_b32 v253, s5, 61
	v_mov_b32_e32 v9, 0
	v_readlane_b32 s2, v253, 29
	v_readlane_b32 s3, v253, 30
	s_mov_b32 s0, 0xf000
	v_add_u32_e32 v42, 0x1000, v128
	v_lshl_add_u64 v[10:11], s[2:3], 0, v[8:9]
	v_and_b32_e32 v8, 1, v150
	v_add_co_u32_e32 v16, vcc, s0, v10
	v_lshlrev_b32_e32 v8, 3, v8
	v_add_u32_e32 v44, 0x1800, v128
	v_add_u32_e32 v46, 0x1c00, v128
	v_addc_co_u32_e32 v17, vcc, 0, v11, vcc
	v_lshl_add_u64 v[18:19], s[2:3], 0, v[8:9]
	v_ashrrev_i32_e32 v43, 31, v42
	v_ashrrev_i32_e32 v45, 31, v44
	v_ashrrev_i32_e32 v47, 31, v46
	v_add_co_u32_e32 v24, vcc, s0, v18
	v_lshl_add_u64 v[0:1], v[128:129], 3, s[2:3]
	v_lshl_add_u64 v[2:3], v[42:43], 3, s[2:3]
	v_lshl_add_u64 v[4:5], v[44:45], 3, s[2:3]
	v_lshl_add_u64 v[6:7], v[46:47], 3, s[2:3]
	v_addc_co_u32_e32 v25, vcc, 0, v19, vcc
	global_load_dwordx2 v[0:1], v[0:1], off
	s_nop 0
	global_load_dwordx2 v[2:3], v[2:3], off
	s_nop 0
	global_load_dwordx2 v[4:5], v[4:5], off
	s_nop 0
	global_load_dwordx2 v[6:7], v[6:7], off
	s_nop 0
	global_load_dwordx2 v[10:11], v[16:17], off
	global_load_dwordx2 v[12:13], v[16:17], off offset:2048
	global_load_dwordx2 v[14:15], v[16:17], off offset:3072
	s_nop 0
	global_load_dwordx2 v[16:17], v[16:17], off offset:3584
	s_nop 0
	global_load_dwordx2 v[18:19], v[24:25], off offset:3840
	global_load_dwordx2 v[20:21], v[24:25], off offset:3968
	global_load_dwordx2 v[22:23], v[24:25], off offset:4032
	s_nop 0
	global_load_dwordx2 v[24:25], v[24:25], off offset:4064
	v_ashrrev_i32_e32 v8, 4, v128
	v_lshlrev_b32_e32 v8, 3, v8
	v_and_b32_e32 v8, -16, v8
	v_lshlrev_b32_e32 v106, 3, v128
	v_add3_u32 v107, 0, v8, v106
	v_ashrrev_i32_e32 v8, 4, v42
	v_lshlrev_b32_e32 v8, 3, v8
	v_add_u32_e32 v28, 0x200, v128
	v_and_b32_e32 v8, -16, v8
	v_add3_u32 v108, 0, v8, v106
	v_ashrrev_i32_e32 v8, 4, v28
	v_lshlrev_b32_e32 v8, 3, v8
	v_and_b32_e32 v8, -16, v8
	v_add3_u32 v109, 0, v8, v106
	v_add_u32_e32 v8, 0x1200, v128
	v_ashrrev_i32_e32 v8, 4, v8
	v_lshlrev_b32_e32 v8, 3, v8
	v_add_u32_e32 v30, 0x400, v128
	v_and_b32_e32 v8, -16, v8
	v_add3_u32 v110, 0, v8, v106
	v_ashrrev_i32_e32 v8, 4, v30
	v_lshlrev_b32_e32 v8, 3, v8
	v_and_b32_e32 v8, -16, v8
	v_add3_u32 v111, 0, v8, v106
	v_add_u32_e32 v8, 0x1400, v128
	v_ashrrev_i32_e32 v8, 4, v8
	v_lshlrev_b32_e32 v8, 3, v8
	v_add_u32_e32 v32, 0x600, v128
	v_and_b32_e32 v8, -16, v8
	v_add3_u32 v112, 0, v8, v106
	v_ashrrev_i32_e32 v8, 4, v32
	v_lshlrev_b32_e32 v8, 3, v8
	v_and_b32_e32 v8, -16, v8
	v_add3_u32 v113, 0, v8, v106
	v_add_u32_e32 v8, 0x1600, v128
	v_ashrrev_i32_e32 v8, 4, v8
	v_lshlrev_b32_e32 v8, 3, v8
	v_add_u32_e32 v34, 0x800, v128
	v_and_b32_e32 v8, -16, v8
	v_add3_u32 v114, 0, v8, v106
	v_ashrrev_i32_e32 v8, 4, v34
	v_lshlrev_b32_e32 v8, 3, v8
	v_and_b32_e32 v8, -16, v8
	v_add3_u32 v115, 0, v8, v106
	v_ashrrev_i32_e32 v8, 4, v44
	v_lshlrev_b32_e32 v8, 3, v8
	s_movk_i32 s0, 0xfff
	v_add_u32_e32 v36, 0xa00, v128
	v_and_b32_e32 v8, -16, v8
	v_cmp_gt_i32_e64 s[6:7], s0, v128
	s_movk_i32 s0, 0xfe00
	v_add3_u32 v116, 0, v8, v106
	v_ashrrev_i32_e32 v8, 4, v36
	v_cmp_lt_i32_e64 s[8:9], s0, v128
	s_movk_i32 s0, 0xdff
	v_lshlrev_b32_e32 v8, 3, v8
	v_cmp_gt_i32_e64 s[10:11], s0, v128
	s_movk_i32 s0, 0xfc00
	v_and_b32_e32 v8, -16, v8
	v_cmp_lt_i32_e64 s[12:13], s0, v128
	s_movk_i32 s0, 0xbff
	v_add3_u32 v117, 0, v8, v106
	v_add_u32_e32 v8, 0x1a00, v128
	v_cmp_gt_i32_e64 s[14:15], s0, v128
	s_movk_i32 s0, 0xfa00
	v_ashrrev_i32_e32 v8, 4, v8
	v_cmp_lt_i32_e64 s[16:17], s0, v128
	s_movk_i32 s0, 0x9ff
	v_lshlrev_b32_e32 v8, 3, v8
	v_cmp_gt_i32_e64 s[18:19], s0, v128
	s_movk_i32 s0, 0xf800
	v_add_u32_e32 v38, 0xc00, v128
	v_and_b32_e32 v8, -16, v8
	v_cmp_lt_i32_e64 s[20:21], s0, v128
	s_movk_i32 s0, 0x7ff
	v_add3_u32 v118, 0, v8, v106
	v_ashrrev_i32_e32 v8, 4, v38
	v_cmp_gt_i32_e64 s[22:23], s0, v128
	s_movk_i32 s0, 0xf600
	v_lshlrev_b32_e32 v8, 3, v8
	v_cmp_lt_i32_e64 s[24:25], s0, v128
	s_movk_i32 s0, 0x5ff
	v_and_b32_e32 v8, -16, v8
	v_cmp_gt_i32_e64 s[26:27], s0, v128
	s_movk_i32 s0, 0xf400
	v_add3_u32 v119, 0, v8, v106
	v_ashrrev_i32_e32 v8, 4, v46
	v_cmp_lt_i32_e64 s[28:29], s0, v128
	s_movk_i32 s0, 0x3ff
	v_lshlrev_b32_e32 v8, 3, v8
	v_cmp_gt_i32_e64 s[30:31], s0, v128
	v_add_u32_e32 v40, 0xe00, v128
	s_movk_i32 s0, 0xf200
	v_and_b32_e32 v8, -16, v8
	v_cmp_lt_i32_e64 s[34:35], s0, v128
	s_movk_i32 s0, 0x1ff
	v_add3_u32 v120, 0, v8, v106
	v_ashrrev_i32_e32 v8, 4, v40
	v_cmp_gt_i32_e64 s[36:37], s0, v128
	v_lshlrev_b32_e32 v8, 3, v8
	v_readlane_b32 s0, v253, 54
	v_and_b32_e32 v8, -16, v8
	v_readlane_b32 s1, v253, 55
	v_add3_u32 v121, 0, v8, v106
	v_add_u32_e32 v8, 0x1e00, v128
	v_lshl_add_u64 v[42:43], v[128:129], 1, s[0:1]
	v_readlane_b32 s0, v253, 0
	v_ashrrev_i32_e32 v8, 4, v8
	s_lshl_b32 s0, s0, 3
	s_mov_b32 s62, 0
	v_lshlrev_b32_e32 v8, 3, v8
	s_and_b32 s0, s0, 0xfffffe00
	s_mov_b32 s58, 0xbec3ef15
	v_and_b32_e32 v8, -16, v8
	v_lshl_add_u32 v123, v150, 3, s0
	v_lshl_add_u64 v[44:45], v[128:129], 2, s[84:85]
	s_mov_b64 s[2:3], 0x23000800
	s_mov_b32 s59, 0xbf6c835e
	s_mov_b32 s63, s62
	s_movk_i32 s57, 0x1000
	v_cmp_lt_i32_e64 s[4:5], 0, v128
	v_mov_b32_e32 v26, v128
	v_mov_b32_e32 v27, v9
	v_mov_b32_e32 v29, v9
	v_mov_b32_e32 v31, v9
	v_mov_b32_e32 v33, v9
	v_mov_b32_e32 v35, v9
	v_mov_b32_e32 v37, v9
	v_mov_b32_e32 v39, v9
	v_mov_b32_e32 v41, v9
	v_add3_u32 v122, 0, v8, v106
	v_sub_u32_e32 v124, 0, v123
	v_sub_u32_e32 v125, 0, v128
	v_lshl_add_u64 v[44:45], v[44:45], 0, s[2:3]
	v_mov_b32_e32 v126, 0x3000
	v_mov_b32_e32 v127, 0x2000
	v_mov_b32_e32 v130, 0x4000
	s_mov_b64 s[48:49], 0x1000
	s_mov_b64 s[50:51], 0x1400
	s_mov_b64 s[52:53], 0x1800
	s_mov_b64 s[54:55], 0x1c00
	s_mov_b32 s92, 0x11000
	s_mov_b32 s93, 0x21000
	s_add_i32 s2, 0, 0x19800
	s_mov_b32 s3, 0x12000
	s_mov_b32 s96, 0x20000
	s_mov_b32 s56, 0xbf3504f3
	s_mov_b32 s97, 0x3f3504f3
	s_mov_b32 s42, 0x3f6c835e
	s_mov_b32 s43, 0x3ec3ef15
	s_mov_b32 s60, s59
	s_mov_b32 s61, s58
	v_mov_b64_e32 v[184:185], s[62:63]
	s_mov_b32 s62, 0x39000000
	v_mov_b32_e32 v186, v9
	v_mov_b32_e32 v187, v9
	s_mov_b32 s63, s76
	v_readlane_b32 s98, v253, 3
	v_mbcnt_lo_u32_b32 v254, -1, 0
	v_mbcnt_hi_u32_b32 v254, -1, v254
	v_lshlrev_b32_e32 v254, 7, v254
	s_lshr_b32 s98, s98, 6
	s_and_b32 s99, s98, 3
	s_mul_i32 s99, s99, 0xc00000
	s_lshr_b32 s100, s98, 2
	s_lshl_b32 s100, s100, 22
	s_add_u32 s99, s99, s100
	s_add_u32 s99, s99, 0xed00000
	v_add_u32_e32 v254, s99, v254
	s_mov_b32 s100, 0
	s_cmp_lt_u32 s98, 4
	s_cselect_b32 s100, 0x800000, s100
	s_add_u32 s100, s84, s100
	s_addc_u32 s101, s85, 0
	v_readlane_b32 s98, v253, 3
	s_nop 3
	s_lshr_b32 s98, s98, 6
	s_and_b32 s99, s98, 1
	s_lshl_b32 s99, s99, 13
	s_lshr_b32 s98, s98, 1
	s_lshl_b32 s98, s98, 23
	s_add_u32 s98, s98, s99
	s_add_u32 s98, s98, 0x23000000
.LBB0_1343:
	s_mov_b32 s64, s63
	v_mbcnt_lo_u32_b32 v255, -1, 0
	v_mbcnt_hi_u32_b32 v255, -1, v255
	v_lshlrev_b32_e32 v255, 7, v255
	s_lshl_b32 s99, s64, 14
	s_add_u32 s99, s99, s98
	v_add_u32_e32 v255, s99, v255
	global_load_dword v255, v255, s[84:85]
	s_lshl_b32 s99, s64, 13
	v_add_u32_e32 v254, s99, v254
	global_load_dword v255, v254, s[84:85]
	global_load_dword v255, v254, s[100:101]
	v_subrev_u32_e32 v254, s99, v254
	s_ashr_i32 s65, s64, 31
	s_lshl_b64 s[70:71], s[64:65], 2
	s_add_u32 s72, s38, s70
	s_addc_u32 s73, s39, s71
	s_add_i32 s66, s64, 0x600
	s_ashr_i32 s67, s66, 31
	s_lshl_b64 s[68:69], s[66:67], 2
	s_add_u32 s68, s38, s68
	s_addc_u32 s69, s39, s69
	global_load_dword v153, v9, s[72:73]
	global_load_dword v154, v9, s[68:69]
	global_load_dword v152, v126, s[72:73]
	s_add_u32 s68, s40, s70
	s_addc_u32 s69, s41, s71
	global_load_dword v47, v9, s[68:69]
	global_load_dword v149, v9, s[72:73] offset:2048
	global_load_dword v151, v127, s[72:73]
	global_load_dword v148, v126, s[72:73] offset:2048
	global_load_dword v86, v9, s[68:69] offset:2048
	s_add_i32 s68, s64, 0x400
	s_ashr_i32 s69, s68, 31
	s_lshl_b64 s[74:75], s[68:69], 2
	s_add_u32 s76, s38, s74
	s_addc_u32 s77, s39, s75
	global_load_dword v133, v9, s[76:77]
	global_load_dword v135, v127, s[72:73] offset:2048
	global_load_dword v134, v130, s[72:73]
	s_add_u32 s72, s40, s74
	s_addc_u32 s73, s41, s75
	s_add_u32 s70, s46, s70
	global_load_dword v131, v9, s[72:73]
	s_addc_u32 s71, s47, s71
	s_lshl_b64 s[72:73], s[64:65], 13
	s_add_u32 s78, s90, s72
	s_addc_u32 s79, s91, s73
	v_lshl_add_u64 v[50:51], v[128:129], 1, s[78:79]
	global_load_dword v87, v9, s[70:71]
	global_load_dword v132, v9, s[70:71] offset:2048
	global_load_ushort v8, v[50:51], off
	s_waitcnt vmcnt(0)
	v_lshlrev_b32_e32 v8, 16, v8
	v_fma_f32 v48, v154, v8, v47
	s_and_saveexec_b64 s[70:71], s[4:5]
	s_cbranch_execz .LBB0_1345
	v_lshl_add_u64 v[52:53], v[26:27], 1, s[78:79]
	global_load_ushort v8, v[52:53], off offset:-2
	s_waitcnt vmcnt(0)
	v_lshlrev_b32_e32 v8, 16, v8
	v_fmac_f32_e32 v48, v153, v8

.LBB0_4120:
	s_or_b64 exec, exec, s[0:1]
	v_readlane_b32 s6, v253, 23
	v_readlane_b32 s7, v253, 24
	s_load_dwordx2 s[0:1], s[6:7], 0x78
	s_waitcnt lgkmcnt(0)
	s_load_dwordx2 s[4:5], s[6:7], 0x80
	s_waitcnt lgkmcnt(0)
	s_load_dwordx2 s[2:3], s[6:7], 0xa8
	s_waitcnt lgkmcnt(0)
	s_nop 0
	s_load_dwordx2 s[2:3], s[6:7], 0xb0
	s_waitcnt lgkmcnt(0)
	s_load_dwordx2 s[6:7], s[6:7], 0xb8
	s_waitcnt lgkmcnt(0)
	s_nop 0
	v_readlane_b32 s2, v253, 52
	v_readlane_b32 s3, v253, 53
	s_andn2_b64 vcc, exec, s[2:3]
	s_nop 0
	v_cndmask_b32_e64 v0, 0, 1, s[2:3]
	v_cmp_ne_u32_e64 s[8:9], 1, v0
	s_nop 1
	v_writelane_b32 v252, s8, 44
	s_nop 1
	v_writelane_b32 v252, s9, 45
	s_cbranch_vccnz .LBB0_4535
	s_add_u32 s47, s0, 0x4800
	s_addc_u32 s53, s1, 0
	s_add_u32 s2, s4, 0x1800
	s_addc_u32 s83, s5, 0
	v_writelane_b32 v253, s2, 44
	s_add_u32 s2, s6, 0x1000
	v_writelane_b32 v253, s2, 17
	s_addc_u32 s2, s7, 0
	v_writelane_b32 v253, s2, 13
	v_and_b32_e32 v8, 31, v150
	v_readlane_b32 s8, v253, 29
	v_readlane_b32 s9, v253, 30
	v_lshlrev_b32_e32 v8, 3, v8
	v_mov_b32_e32 v9, 0
	v_lshl_add_u64 v[10:11], s[8:9], 0, v[8:9]
	s_mov_b32 s2, 0xf000
	v_and_b32_e32 v8, 1, v150
	v_add_co_u32_e32 v16, vcc, s2, v10
	v_lshlrev_b32_e32 v8, 3, v8
	v_add_u32_e32 v40, 0x1000, v128
	v_add_u32_e32 v42, 0x1800, v128
	v_add_u32_e32 v44, 0x1c00, v128
	v_addc_co_u32_e32 v17, vcc, 0, v11, vcc
	v_lshl_add_u64 v[18:19], s[8:9], 0, v[8:9]
	v_ashrrev_i32_e32 v41, 31, v40
	v_ashrrev_i32_e32 v43, 31, v42
	v_ashrrev_i32_e32 v45, 31, v44
	v_add_co_u32_e32 v24, vcc, s2, v18
	v_lshl_add_u64 v[0:1], v[128:129], 3, s[8:9]
	v_lshl_add_u64 v[2:3], v[40:41], 3, s[8:9]
	v_lshl_add_u64 v[4:5], v[42:43], 3, s[8:9]
	v_lshl_add_u64 v[6:7], v[44:45], 3, s[8:9]
	v_addc_co_u32_e32 v25, vcc, 0, v19, vcc
	global_load_dwordx2 v[0:1], v[0:1], off
	s_nop 0
	global_load_dwordx2 v[2:3], v[2:3], off
	s_nop 0
	global_load_dwordx2 v[4:5], v[4:5], off
	s_nop 0
	global_load_dwordx2 v[6:7], v[6:7], off
	s_nop 0
	global_load_dwordx2 v[10:11], v[16:17], off
	global_load_dwordx2 v[12:13], v[16:17], off offset:2048
	global_load_dwordx2 v[14:15], v[16:17], off offset:3072
	s_nop 0
	global_load_dwordx2 v[16:17], v[16:17], off offset:3584
	s_nop 0
	global_load_dwordx2 v[18:19], v[24:25], off offset:3840
	global_load_dwordx2 v[20:21], v[24:25], off offset:3968
	global_load_dwordx2 v[22:23], v[24:25], off offset:4032
	s_nop 0
	global_load_dwordx2 v[24:25], v[24:25], off offset:4064
	v_ashrrev_i32_e32 v8, 4, v128
	v_lshlrev_b32_e32 v8, 3, v8
	v_and_b32_e32 v8, -16, v8
	v_lshlrev_b32_e32 v41, 3, v128
	v_add3_u32 v104, 0, v8, v41
	v_ashrrev_i32_e32 v8, 4, v40
	v_lshlrev_b32_e32 v8, 3, v8
	v_add_u32_e32 v26, 0x200, v128
	v_and_b32_e32 v8, -16, v8
	v_add3_u32 v105, 0, v8, v41
	v_ashrrev_i32_e32 v8, 4, v26
	v_lshlrev_b32_e32 v8, 3, v8
	v_and_b32_e32 v8, -16, v8
	v_add3_u32 v106, 0, v8, v41
	v_add_u32_e32 v8, 0x1200, v128
	v_ashrrev_i32_e32 v8, 4, v8
	v_lshlrev_b32_e32 v8, 3, v8
	v_add_u32_e32 v28, 0x400, v128
	v_and_b32_e32 v8, -16, v8
	v_add3_u32 v107, 0, v8, v41
	v_ashrrev_i32_e32 v8, 4, v28
	v_lshlrev_b32_e32 v8, 3, v8
	v_and_b32_e32 v8, -16, v8
	v_add3_u32 v108, 0, v8, v41
	v_add_u32_e32 v8, 0x1400, v128
	v_ashrrev_i32_e32 v8, 4, v8
	v_lshlrev_b32_e32 v8, 3, v8
	v_add_u32_e32 v30, 0x600, v128
	v_and_b32_e32 v8, -16, v8
	v_add3_u32 v109, 0, v8, v41
	v_ashrrev_i32_e32 v8, 4, v30
	v_lshlrev_b32_e32 v8, 3, v8
	v_and_b32_e32 v8, -16, v8
	v_add3_u32 v110, 0, v8, v41
	v_add_u32_e32 v8, 0x1600, v128
	v_ashrrev_i32_e32 v8, 4, v8
	v_lshlrev_b32_e32 v8, 3, v8
	v_add_u32_e32 v32, 0x800, v128
	v_and_b32_e32 v8, -16, v8
	v_add3_u32 v111, 0, v8, v41
	v_ashrrev_i32_e32 v8, 4, v32
	v_lshlrev_b32_e32 v8, 3, v8
	v_and_b32_e32 v8, -16, v8
	v_add3_u32 v112, 0, v8, v41
	v_ashrrev_i32_e32 v8, 4, v42
	v_lshlrev_b32_e32 v8, 3, v8
	v_add_u32_e32 v34, 0xa00, v128
	v_and_b32_e32 v8, -16, v8
	v_add3_u32 v113, 0, v8, v41
	v_ashrrev_i32_e32 v8, 4, v34
	v_lshlrev_b32_e32 v8, 3, v8
	v_and_b32_e32 v8, -16, v8
	s_movk_i32 s2, 0xfff
	v_add3_u32 v114, 0, v8, v41
	v_add_u32_e32 v8, 0x1a00, v128
	v_cmp_gt_i32_e64 s[10:11], s2, v128
	s_movk_i32 s2, 0xfe00
	v_ashrrev_i32_e32 v8, 4, v8
	v_cmp_lt_i32_e64 s[12:13], s2, v128
	s_movk_i32 s2, 0xdff
	v_lshlrev_b32_e32 v8, 3, v8
	v_cmp_gt_i32_e64 s[14:15], s2, v128
	s_movk_i32 s2, 0xfc00
	v_add_u32_e32 v36, 0xc00, v128
	v_and_b32_e32 v8, -16, v8
	v_cmp_lt_i32_e64 s[16:17], s2, v128
	s_movk_i32 s2, 0xbff
	v_add3_u32 v115, 0, v8, v41
	v_ashrrev_i32_e32 v8, 4, v36
	v_cmp_gt_i32_e64 s[18:19], s2, v128
	s_movk_i32 s2, 0xfa00
	v_lshlrev_b32_e32 v8, 3, v8
	v_cmp_lt_i32_e64 s[20:21], s2, v128
	s_movk_i32 s2, 0x9ff
	v_and_b32_e32 v8, -16, v8
	v_cmp_gt_i32_e64 s[22:23], s2, v128
	s_movk_i32 s2, 0xf800
	v_add3_u32 v116, 0, v8, v41
	v_ashrrev_i32_e32 v8, 4, v44
	v_cmp_lt_i32_e64 s[24:25], s2, v128
	s_movk_i32 s2, 0x7ff
	v_lshlrev_b32_e32 v8, 3, v8
	v_cmp_gt_i32_e64 s[26:27], s2, v128
	s_movk_i32 s2, 0xf600
	v_add_u32_e32 v38, 0xe00, v128
	v_and_b32_e32 v8, -16, v8
	v_cmp_lt_i32_e64 s[28:29], s2, v128
	s_movk_i32 s2, 0x5ff
	v_add3_u32 v117, 0, v8, v41
	v_ashrrev_i32_e32 v8, 4, v38
	v_cmp_gt_i32_e64 s[30:31], s2, v128
	s_movk_i32 s2, 0xf400
	v_lshlrev_b32_e32 v8, 3, v8
	v_cmp_lt_i32_e64 s[34:35], s2, v128
	s_movk_i32 s2, 0x3ff
	v_and_b32_e32 v8, -16, v8
	v_cmp_gt_i32_e64 s[36:37], s2, v128
	s_movk_i32 s2, 0xf200
	v_add3_u32 v118, 0, v8, v41
	v_add_u32_e32 v8, 0x1e00, v128
	v_cmp_lt_i32_e64 s[38:39], s2, v128
	s_movk_i32 s2, 0x1ff
	v_ashrrev_i32_e32 v8, 4, v8
	v_cmp_gt_i32_e64 s[40:41], s2, v128
	v_lshlrev_b32_e32 v8, 3, v8
	v_readlane_b32 s2, v253, 54
	v_and_b32_e32 v8, -16, v8
	v_readlane_b32 s3, v253, 55
	v_add3_u32 v119, 0, v8, v41
	s_mov_b32 s6, 0
	v_lshl_add_u64 v[40:41], v[128:129], 1, s[2:3]
	v_readlane_b32 s2, v253, 0
	s_lshl_b32 s2, s2, 3
	s_and_b32 s2, s2, 0xfffffe00
	s_mov_b32 s48, 0xbec3ef15
	s_mov_b32 s7, s6
	v_lshl_add_u32 v120, v150, 3, s2
	v_lshl_add_u64 v[42:43], v[128:129], 2, s[84:85]
	s_mov_b64 s[2:3], 0x23000800
	s_mov_b32 s49, 0xbf6c835e
	v_mov_b64_e32 v[180:181], s[6:7]
	v_readlane_b32 s6, v253, 58
	s_mov_b64 s[0:1], 0x1800
	s_mov_b64 s[4:5], 0x1000
	v_cmp_lt_i32_e64 s[8:9], 0, v128
	s_movk_i32 s33, 0x200
	v_mov_b32_e32 v27, v9
	v_mov_b32_e32 v29, v9
	v_mov_b32_e32 v31, v9
	v_mov_b32_e32 v33, v9
	v_mov_b32_e32 v35, v9
	v_mov_b32_e32 v37, v9
	v_mov_b32_e32 v39, v9
	v_sub_u32_e32 v121, 0, v120
	v_sub_u32_e32 v122, 0, v128
	v_lshl_add_u64 v[42:43], v[42:43], 0, s[2:3]
	v_mov_b32_e32 v123, 0x3000
	v_mov_b32_e32 v124, 0x2000
	v_mov_b32_e32 v125, 0x4000
	s_mov_b64 s[42:43], 0x1400
	s_mov_b64 s[44:45], 0x1c00
	s_mov_b32 s88, 0x11000
	s_mov_b32 s89, 0x21000
	s_add_i32 s96, 0, 0x19800
	s_mov_b32 s97, 0x12000
	s_mov_b32 s92, 0x20000
	s_mov_b32 s46, 0xbf3504f3
	s_mov_b32 s93, 0x3f3504f3
	s_mov_b32 s2, 0x3f6c835e
	s_mov_b32 s3, 0x3ec3ef15
	s_mov_b32 s50, s49
	s_mov_b32 s51, s48
	s_mov_b32 s52, 0x39000000
	v_mov_b32_e32 v182, v9
	v_mov_b32_e32 v183, v9
	s_mov_b32 s82, s6
	v_readlane_b32 s7, v253, 59
	v_readlane_b32 s98, v253, 3
	v_mbcnt_lo_u32_b32 v254, -1, 0
	v_mbcnt_hi_u32_b32 v254, -1, v254
	v_lshlrev_b32_e32 v254, 7, v254
	s_lshr_b32 s98, s98, 6
	s_and_b32 s99, s98, 3
	s_mul_i32 s99, s99, 0xc00000
	s_lshr_b32 s100, s98, 2
	s_lshl_b32 s100, s100, 22
	s_add_u32 s99, s99, s100
	s_add_u32 s99, s99, 0xed00000
	v_add_u32_e32 v254, s99, v254
	s_mov_b32 s100, 0
	s_cmp_lt_u32 s98, 4
	s_cselect_b32 s100, 0x800000, s100
	s_add_u32 s100, s84, s100
	s_addc_u32 s101, s85, 0
	v_readlane_b32 s98, v253, 3
	s_nop 3
	s_lshr_b32 s98, s98, 6
	s_and_b32 s99, s98, 1
	s_lshl_b32 s99, s99, 13
	s_lshr_b32 s98, s98, 1
	s_lshl_b32 s98, s98, 23
	s_add_u32 s98, s98, s99
	s_add_u32 s98, s98, 0x23000000
.LBB0_4122:
	s_mov_b32 s54, s82
	v_mbcnt_lo_u32_b32 v255, -1, 0
	v_mbcnt_hi_u32_b32 v255, -1, v255
	v_lshlrev_b32_e32 v255, 7, v255
	s_lshl_b32 s99, s54, 14
	s_add_u32 s99, s99, s98
	v_add_u32_e32 v255, s99, v255
	global_load_dword v255, v255, s[84:85]
	s_lshl_b32 s99, s54, 13
	v_add_u32_e32 v254, s99, v254
	global_load_dword v255, v254, s[84:85]
	global_load_dword v255, v254, s[100:101]
	v_subrev_u32_e32 v254, s99, v254
	s_ashr_i32 s55, s54, 31
	s_lshl_b64 s[6:7], s[54:55], 2
	s_add_u32 s66, s47, s6
	s_addc_u32 s67, s53, s7
	s_add_i32 s56, s54, 0x600
	s_ashr_i32 s57, s56, 31
	s_lshl_b64 s[58:59], s[56:57], 2
	s_add_u32 s58, s47, s58
	s_addc_u32 s59, s53, s59
	v_readlane_b32 s76, v253, 44
	global_load_dword v149, v9, s[66:67]
	global_load_dword v150, v9, s[58:59]
	global_load_dword v148, v123, s[66:67]
	s_add_u32 s58, s76, s6
	s_addc_u32 s59, s83, s7
	s_add_i32 s72, s54, 0x200
	s_ashr_i32 s73, s72, 31
	s_lshl_b64 s[68:69], s[72:73], 2
	global_load_dword v45, v9, s[58:59]
	s_add_u32 s58, s47, s68
	s_addc_u32 s59, s53, s69
	global_load_dword v146, v9, s[58:59]
	global_load_dword v147, v124, s[66:67]
	global_load_dword v145, v123, s[66:67] offset:2048
	s_add_u32 s58, s76, s68
	s_addc_u32 s59, s83, s69
	global_load_dword v84, v9, s[58:59]
	s_add_i32 s58, s54, 0x400
	s_ashr_i32 s59, s58, 31
	s_lshl_b64 s[70:71], s[58:59], 2
	s_add_u32 s74, s47, s70
	s_addc_u32 s75, s53, s71
	global_load_dword v130, v9, s[74:75]
	global_load_dword v132, v124, s[66:67] offset:2048
	global_load_dword v131, v125, s[66:67]
	s_add_u32 s66, s76, s70
	s_addc_u32 s67, s83, s71
	global_load_dword v126, v9, s[66:67]
	v_readlane_b32 s66, v253, 17
	s_add_u32 s6, s66, s6
	v_readlane_b32 s67, v253, 13
	s_addc_u32 s7, s67, s7
	global_load_dword v85, v9, s[6:7]
	s_add_u32 s6, s66, s68
	s_addc_u32 s7, s67, s69
	s_lshl_b64 s[68:69], s[54:55], 13
	global_load_dword v127, v9, s[6:7]
	s_add_u32 s6, s90, s68
	s_addc_u32 s7, s91, s69
	v_lshl_add_u64 v[48:49], v[128:129], 1, s[6:7]
	global_load_ushort v8, v[48:49], off
	s_waitcnt vmcnt(0)
	v_lshlrev_b32_e32 v8, 16, v8
	v_fma_f32 v46, v150, v8, v45
	s_and_saveexec_b64 s[66:67], s[8:9]
	s_cbranch_execz .LBB0_4124
	global_load_ushort v8, v[48:49], off offset:-2
	s_waitcnt vmcnt(0)
	v_lshlrev_b32_e32 v8, 16, v8
	v_fmac_f32_e32 v46, v149, v8
